# prep units: half 1 takes wave roles rotated by one in the KK/solve/output stages so each SIMD hosts one two-block and one one-block wave; solver stays on its own SIMD
# speedup vs baseline: 1.0043x; 1.0043x over previous
.Lsb_nopend:
	s_barrier
	ds_read_b32 v0, v158
	v_lshlrev_b32_e32 v60, 6, v147
	v_xor_b32_e32 v60, v60, v148
	v_ashrrev_i32_e32 v51, 6, v60
	v_and_b32_e32 v52, 31, v148
	v_and_b32_e32 v59, 1, v51
	v_lshrrev_b32_e32 v53, 5, v160
	v_lshl_or_b32 v55, v59, 5, v52
	v_ashrrev_i32_e32 v60, 7, v60
	v_cmp_ne_u32_e64 s[44:45], 1, v51
	v_mov_b32_e32 v2, 0
	v_lshlrev_b32_e32 v54, 4, v53
	v_mul_u32_u24_e32 v18, 0x110, v55
	v_mov_b32_e32 v3, 0
	v_mov_b32_e32 v4, 0
	v_mov_b32_e32 v5, 0
	v_mov_b32_e32 v6, 0
	v_mov_b32_e32 v7, 0
	v_mov_b32_e32 v8, 0
	v_mov_b32_e32 v9, 0
	v_mov_b32_e32 v10, 0
	v_mov_b32_e32 v11, 0
	v_mov_b32_e32 v12, 0
	v_mov_b32_e32 v13, 0
	v_mov_b32_e32 v14, 0
	v_mov_b32_e32 v15, 0
	v_mov_b32_e32 v16, 0
	v_mov_b32_e32 v17, 0
	s_and_saveexec_b64 s[0:1], s[44:45]
	s_cbranch_execz .LBB0_600
	v_lshl_or_b32 v2, v60, 5, v52
	v_mul_lo_u32 v2, v2, s14
	v_add3_u32 v10, v146, v2, v54
	v_add3_u32 v11, v146, v18, v54
	ds_read_b128 v[2:5], v10 offset:17408
	ds_read_b128 v[20:23], v10 offset:17440
	ds_read_b128 v[6:9], v11 offset:17408
	ds_read_b128 v[24:27], v11 offset:17440
	ds_read_b128 v[28:31], v10 offset:17472
	ds_read_b128 v[32:35], v10 offset:17504
	ds_read_b128 v[36:39], v11 offset:17472
	ds_read_b128 v[40:43], v11 offset:17504
	ds_read_b128 v[44:47], v10 offset:17536
	ds_read_b128 v[62:65], v10 offset:17568
	ds_read_b128 v[66:69], v11 offset:17536
	ds_read_b128 v[70:73], v11 offset:17568
	ds_read_b128 v[74:77], v10 offset:17600
	ds_read_b128 v[78:81], v10 offset:17632
	ds_read_b128 v[82:85], v11 offset:17600
	ds_read_b128 v[86:89], v11 offset:17632
	s_waitcnt lgkmcnt(13)
	v_mfma_f32_32x32x16_bf16 v[2:17], v[2:5], v[6:9], 0
	s_waitcnt lgkmcnt(12)
	v_mfma_f32_32x32x16_bf16 v[2:17], v[20:23], v[24:27], v[2:17]
	s_waitcnt lgkmcnt(9)
	v_mfma_f32_32x32x16_bf16 v[2:17], v[28:31], v[36:39], v[2:17]
	s_waitcnt lgkmcnt(8)
	v_mfma_f32_32x32x16_bf16 v[2:17], v[32:35], v[40:43], v[2:17]
	s_waitcnt lgkmcnt(5)
	v_mfma_f32_32x32x16_bf16 v[2:17], v[44:47], v[66:69], v[2:17]
	s_waitcnt lgkmcnt(4)
	v_mfma_f32_32x32x16_bf16 v[2:17], v[62:65], v[70:73], v[2:17]
	s_waitcnt lgkmcnt(1)
	v_mfma_f32_32x32x16_bf16 v[2:17], v[74:77], v[82:85], v[2:17]
	s_waitcnt lgkmcnt(0)
	v_mfma_f32_32x32x16_bf16 v[2:17], v[78:81], v[86:89], v[2:17]

.LBB0_608:
	s_or_b64 exec, exec, s[0:1]
	s_waitcnt lgkmcnt(0)
	s_barrier
	v_lshrrev_b32_e32 v30, 6, v148
	v_cmp_ne_u32_e32 vcc, v30, v147
	v_lshlrev_b32_e32 v30, 3, v53
	s_and_saveexec_b64 s[0:1], vcc
	s_xor_b64 s[0:1], exec, s[0:1]
	v_lshlrev_b32_e32 v30, 3, v53
	s_andn2_saveexec_b64 s[0:1], s[0:1]
	s_cbranch_execz .LBB0_618
	s_movk_i32 s2, 0x2080
	v_mad_u32_u24 v106, v53, s2, v146
	v_mov_b32_e32 v70, 0
	v_mov_b32_e32 v71, 0
	v_mov_b32_e32 v72, 0
	v_mov_b32_e32 v73, 0
	v_mov_b32_e32 v74, 0
	v_mov_b32_e32 v75, 0
	v_mov_b32_e32 v76, 0
	v_mov_b32_e32 v77, 0
	v_mov_b32_e32 v78, 0
	v_mov_b32_e32 v79, 0
	v_mov_b32_e32 v80, 0
	v_mov_b32_e32 v81, 0
	v_mov_b32_e32 v82, 0
	v_mov_b32_e32 v83, 0
	v_mov_b32_e32 v84, 0
	v_mov_b32_e32 v85, 0
	v_mov_b32_e32 v86, 0
	v_mov_b32_e32 v87, 0
	v_mov_b32_e32 v88, 0
	v_mov_b32_e32 v89, 0
	v_mov_b32_e32 v90, 0
	v_mov_b32_e32 v91, 0
	v_mov_b32_e32 v92, 0
	v_mov_b32_e32 v93, 0
	v_mov_b32_e32 v94, 0
	v_mov_b32_e32 v95, 0
	v_mov_b32_e32 v96, 0
	v_mov_b32_e32 v97, 0
	v_mov_b32_e32 v98, 0
	v_mov_b32_e32 v99, 0
	v_mov_b32_e32 v100, 0
	v_mov_b32_e32 v101, 0
	ds_read_b128 v[2:5], v106 offset:256
	v_cmp_eq_u32_e32 vcc, 0, v52
	s_nop 1
	v_cndmask_b32_e64 v70, 0, 1.0, vcc
	ds_read_b128 v[6:9], v106 offset:512
	s_waitcnt lgkmcnt(1)
	v_pk_mul_f32 v[102:103], v[70:71], v[2:3]
	v_cmp_eq_u32_e32 vcc, 1, v52
	v_add_f32_e32 v68, v102, v103
	s_nop 0
	v_cndmask_b32_e64 v55, 0, 1.0, vcc
	v_sub_f32_e32 v71, v55, v68
	ds_read_b128 v[10:13], v106 offset:768
	s_waitcnt lgkmcnt(1)
	v_pk_mul_f32 v[102:103], v[70:71], v[6:7]
	v_cmp_eq_u32_e32 vcc, 2, v52
	v_add_f32_e32 v68, v102, v103
	s_nop 0
	v_cndmask_b32_e64 v55, 0, 1.0, vcc
	v_sub_f32_e32 v72, v55, v68
	ds_read_b128 v[14:17], v106 offset:1024
	s_waitcnt lgkmcnt(1)
	v_pk_mul_f32 v[102:103], v[70:71], v[10:11]
	v_pk_mul_f32 v[104:105], v[72:73], v[12:13]
	v_cmp_eq_u32_e32 vcc, 3, v52
	v_add_f32_e32 v68, v102, v103
	v_add_f32_e32 v69, v105, v104
	v_cndmask_b32_e64 v55, 0, 1.0, vcc
	v_add_f32_e32 v68, v68, v69
	v_sub_f32_e32 v73, v55, v68
	ds_read_b128 v[18:21], v106 offset:1280
	ds_read_b128 v[22:25], v106 offset:1296
	s_waitcnt lgkmcnt(2)
	v_pk_mul_f32 v[102:103], v[70:71], v[14:15]
	v_pk_mul_f32 v[104:105], v[72:73], v[16:17]
	v_cmp_eq_u32_e32 vcc, 4, v52
	v_add_f32_e32 v68, v102, v103
	v_add_f32_e32 v69, v105, v104
	v_cndmask_b32_e64 v55, 0, 1.0, vcc
	v_add_f32_e32 v68, v68, v69
	v_sub_f32_e32 v74, v55, v68
	ds_read_b128 v[26:29], v106 offset:1536
	ds_read_b128 v[32:35], v106 offset:1552
	s_waitcnt lgkmcnt(3)
	v_pk_mul_f32 v[102:103], v[70:71], v[18:19]
	v_pk_mul_f32 v[104:105], v[72:73], v[20:21]
	s_waitcnt lgkmcnt(2)
	v_pk_fma_f32 v[102:103], v[74:75], v[22:23], v[102:103]
	v_cmp_eq_u32_e32 vcc, 5, v52
	v_add_f32_e32 v68, v102, v103
	v_add_f32_e32 v69, v105, v104
	v_cndmask_b32_e64 v55, 0, 1.0, vcc
	v_add_f32_e32 v68, v68, v69
	v_sub_f32_e32 v75, v55, v68
	ds_read_b128 v[36:39], v106 offset:1792
	ds_read_b128 v[40:43], v106 offset:1808
	s_waitcnt lgkmcnt(3)
	v_pk_mul_f32 v[102:103], v[70:71], v[26:27]
	v_pk_mul_f32 v[104:105], v[72:73], v[28:29]
	s_waitcnt lgkmcnt(2)
	v_pk_fma_f32 v[102:103], v[74:75], v[32:33], v[102:103]
	v_cmp_eq_u32_e32 vcc, 6, v52
	v_add_f32_e32 v68, v102, v103
	v_add_f32_e32 v69, v105, v104
	v_cndmask_b32_e64 v55, 0, 1.0, vcc
	v_add_f32_e32 v68, v68, v69
	v_sub_f32_e32 v76, v55, v68
	ds_read_b128 v[56:59], v106 offset:2048
	ds_read_b128 v[60:63], v106 offset:2064
	s_waitcnt lgkmcnt(3)
	v_pk_mul_f32 v[102:103], v[70:71], v[36:37]
	v_pk_mul_f32 v[104:105], v[72:73], v[38:39]
	s_waitcnt lgkmcnt(2)
	v_pk_fma_f32 v[102:103], v[74:75], v[40:41], v[102:103]
	v_pk_fma_f32 v[104:105], v[76:77], v[42:43], v[104:105]
	v_cmp_eq_u32_e32 vcc, 7, v52
	v_add_f32_e32 v68, v102, v103
	v_add_f32_e32 v69, v105, v104
	v_cndmask_b32_e64 v55, 0, 1.0, vcc
	v_add_f32_e32 v68, v68, v69
	v_sub_f32_e32 v77, v55, v68
	ds_read_b128 v[64:67], v106 offset:2304
	ds_read_b128 v[2:5], v106 offset:2320
	ds_read_b128 v[6:9], v106 offset:2336
	s_waitcnt lgkmcnt(4)
	v_pk_mul_f32 v[102:103], v[70:71], v[56:57]
	v_pk_mul_f32 v[104:105], v[72:73], v[58:59]
	s_waitcnt lgkmcnt(3)
	v_pk_fma_f32 v[102:103], v[74:75], v[60:61], v[102:103]
	v_pk_fma_f32 v[104:105], v[76:77], v[62:63], v[104:105]
	v_cmp_eq_u32_e32 vcc, 8, v52
	v_add_f32_e32 v68, v102, v103
	v_add_f32_e32 v69, v105, v104
	v_cndmask_b32_e64 v55, 0, 1.0, vcc
	v_add_f32_e32 v68, v68, v69
	v_sub_f32_e32 v78, v55, v68
	ds_read_b128 v[10:13], v106 offset:2560
	ds_read_b128 v[14:17], v106 offset:2576
	ds_read_b128 v[18:21], v106 offset:2592
	s_waitcnt lgkmcnt(5)
	v_pk_mul_f32 v[102:103], v[70:71], v[64:65]
	v_pk_mul_f32 v[104:105], v[72:73], v[66:67]
	s_waitcnt lgkmcnt(4)
	v_pk_fma_f32 v[102:103], v[74:75], v[2:3], v[102:103]
	v_pk_fma_f32 v[104:105], v[76:77], v[4:5], v[104:105]
	s_waitcnt lgkmcnt(3)
	v_pk_fma_f32 v[102:103], v[78:79], v[6:7], v[102:103]
	v_cmp_eq_u32_e32 vcc, 9, v52
	v_add_f32_e32 v68, v102, v103
	v_add_f32_e32 v69, v105, v104
	v_cndmask_b32_e64 v55, 0, 1.0, vcc
	v_add_f32_e32 v68, v68, v69
	v_sub_f32_e32 v79, v55, v68
	ds_read_b128 v[22:25], v106 offset:2816
	ds_read_b128 v[26:29], v106 offset:2832
	ds_read_b128 v[32:35], v106 offset:2848
	s_waitcnt lgkmcnt(5)
	v_pk_mul_f32 v[102:103], v[70:71], v[10:11]
	v_pk_mul_f32 v[104:105], v[72:73], v[12:13]
	s_waitcnt lgkmcnt(4)
	v_pk_fma_f32 v[102:103], v[74:75], v[14:15], v[102:103]
	v_pk_fma_f32 v[104:105], v[76:77], v[16:17], v[104:105]
	s_waitcnt lgkmcnt(3)
	v_pk_fma_f32 v[102:103], v[78:79], v[18:19], v[102:103]
	v_cmp_eq_u32_e32 vcc, 10, v52
	v_add_f32_e32 v68, v102, v103
	v_add_f32_e32 v69, v105, v104
	v_cndmask_b32_e64 v55, 0, 1.0, vcc
	v_add_f32_e32 v68, v68, v69
	v_sub_f32_e32 v80, v55, v68
	ds_read_b128 v[36:39], v106 offset:3072
	ds_read_b128 v[40:43], v106 offset:3088
	ds_read_b128 v[56:59], v106 offset:3104
	s_waitcnt lgkmcnt(5)
	v_pk_mul_f32 v[102:103], v[70:71], v[22:23]
	v_pk_mul_f32 v[104:105], v[72:73], v[24:25]
	s_waitcnt lgkmcnt(4)
	v_pk_fma_f32 v[102:103], v[74:75], v[26:27], v[102:103]
	v_pk_fma_f32 v[104:105], v[76:77], v[28:29], v[104:105]
	s_waitcnt lgkmcnt(3)
	v_pk_fma_f32 v[102:103], v[78:79], v[32:33], v[102:103]
	v_pk_fma_f32 v[104:105], v[80:81], v[34:35], v[104:105]
	v_cmp_eq_u32_e32 vcc, 11, v52
	v_add_f32_e32 v68, v102, v103
	v_add_f32_e32 v69, v105, v104
	v_cndmask_b32_e64 v55, 0, 1.0, vcc
	v_add_f32_e32 v68, v68, v69
	v_sub_f32_e32 v81, v55, v68
	ds_read_b128 v[60:63], v106 offset:3328
	ds_read_b128 v[64:67], v106 offset:3344
	ds_read_b128 v[2:5], v106 offset:3360
	ds_read_b128 v[6:9], v106 offset:3376
	s_waitcnt lgkmcnt(6)
	v_pk_mul_f32 v[102:103], v[70:71], v[36:37]
	v_pk_mul_f32 v[104:105], v[72:73], v[38:39]
	s_waitcnt lgkmcnt(5)
	v_pk_fma_f32 v[102:103], v[74:75], v[40:41], v[102:103]
	v_pk_fma_f32 v[104:105], v[76:77], v[42:43], v[104:105]
	s_waitcnt lgkmcnt(4)
	v_pk_fma_f32 v[102:103], v[78:79], v[56:57], v[102:103]
	v_pk_fma_f32 v[104:105], v[80:81], v[58:59], v[104:105]
	v_cmp_eq_u32_e32 vcc, 12, v52
	v_add_f32_e32 v68, v102, v103
	v_add_f32_e32 v69, v105, v104
	v_cndmask_b32_e64 v55, 0, 1.0, vcc
	v_add_f32_e32 v68, v68, v69
	v_sub_f32_e32 v82, v55, v68
	ds_read_b128 v[10:13], v106 offset:3584
	ds_read_b128 v[14:17], v106 offset:3600
	ds_read_b128 v[18:21], v106 offset:3616
	ds_read_b128 v[22:25], v106 offset:3632
	s_waitcnt lgkmcnt(7)
	v_pk_mul_f32 v[102:103], v[70:71], v[60:61]
	v_pk_mul_f32 v[104:105], v[72:73], v[62:63]
	s_waitcnt lgkmcnt(6)
	v_pk_fma_f32 v[102:103], v[74:75], v[64:65], v[102:103]
	v_pk_fma_f32 v[104:105], v[76:77], v[66:67], v[104:105]
	s_waitcnt lgkmcnt(5)
	v_pk_fma_f32 v[102:103], v[78:79], v[2:3], v[102:103]
	v_pk_fma_f32 v[104:105], v[80:81], v[4:5], v[104:105]
	s_waitcnt lgkmcnt(4)
	v_pk_fma_f32 v[102:103], v[82:83], v[6:7], v[102:103]
	v_cmp_eq_u32_e32 vcc, 13, v52
	v_add_f32_e32 v68, v102, v103
	v_add_f32_e32 v69, v105, v104
	v_cndmask_b32_e64 v55, 0, 1.0, vcc
	v_add_f32_e32 v68, v68, v69
	v_sub_f32_e32 v83, v55, v68
	ds_read_b128 v[26:29], v106 offset:3840
	ds_read_b128 v[32:35], v106 offset:3856
	ds_read_b128 v[36:39], v106 offset:3872
	ds_read_b128 v[40:43], v106 offset:3888
	s_waitcnt lgkmcnt(7)
	v_pk_mul_f32 v[102:103], v[70:71], v[10:11]
	v_pk_mul_f32 v[104:105], v[72:73], v[12:13]
	s_waitcnt lgkmcnt(6)
	v_pk_fma_f32 v[102:103], v[74:75], v[14:15], v[102:103]
	v_pk_fma_f32 v[104:105], v[76:77], v[16:17], v[104:105]
	s_waitcnt lgkmcnt(5)
	v_pk_fma_f32 v[102:103], v[78:79], v[18:19], v[102:103]
	v_pk_fma_f32 v[104:105], v[80:81], v[20:21], v[104:105]
	s_waitcnt lgkmcnt(4)
	v_pk_fma_f32 v[102:103], v[82:83], v[22:23], v[102:103]
	v_cmp_eq_u32_e32 vcc, 14, v52
	v_add_f32_e32 v68, v102, v103
	v_add_f32_e32 v69, v105, v104
	v_cndmask_b32_e64 v55, 0, 1.0, vcc
	v_add_f32_e32 v68, v68, v69
	v_sub_f32_e32 v84, v55, v68
	ds_read_b128 v[56:59], v106 offset:4096
	ds_read_b128 v[60:63], v106 offset:4112
	ds_read_b128 v[64:67], v106 offset:4128
	ds_read_b128 v[2:5], v106 offset:4144
	s_waitcnt lgkmcnt(7)
	v_pk_mul_f32 v[102:103], v[70:71], v[26:27]
	v_pk_mul_f32 v[104:105], v[72:73], v[28:29]
	s_waitcnt lgkmcnt(6)
	v_pk_fma_f32 v[102:103], v[74:75], v[32:33], v[102:103]
	v_pk_fma_f32 v[104:105], v[76:77], v[34:35], v[104:105]
	s_waitcnt lgkmcnt(5)
	v_pk_fma_f32 v[102:103], v[78:79], v[36:37], v[102:103]
	v_pk_fma_f32 v[104:105], v[80:81], v[38:39], v[104:105]
	s_waitcnt lgkmcnt(4)
	v_pk_fma_f32 v[102:103], v[82:83], v[40:41], v[102:103]
	v_pk_fma_f32 v[104:105], v[84:85], v[42:43], v[104:105]
	v_cmp_eq_u32_e32 vcc, 15, v52
	v_add_f32_e32 v68, v102, v103
	v_add_f32_e32 v69, v105, v104
	v_cndmask_b32_e64 v55, 0, 1.0, vcc
	v_add_f32_e32 v68, v68, v69
	v_sub_f32_e32 v85, v55, v68
	ds_read_b128 v[6:9], v106 offset:4352
	ds_read_b128 v[10:13], v106 offset:4368
	ds_read_b128 v[14:17], v106 offset:4384
	ds_read_b128 v[18:21], v106 offset:4400
	ds_read_b128 v[22:25], v106 offset:4416
	s_waitcnt lgkmcnt(8)
	v_pk_mul_f32 v[102:103], v[70:71], v[56:57]
	v_pk_mul_f32 v[104:105], v[72:73], v[58:59]
	s_waitcnt lgkmcnt(7)
	v_pk_fma_f32 v[102:103], v[74:75], v[60:61], v[102:103]
	v_pk_fma_f32 v[104:105], v[76:77], v[62:63], v[104:105]
	s_waitcnt lgkmcnt(6)
	v_pk_fma_f32 v[102:103], v[78:79], v[64:65], v[102:103]
	v_pk_fma_f32 v[104:105], v[80:81], v[66:67], v[104:105]
	s_waitcnt lgkmcnt(5)
	v_pk_fma_f32 v[102:103], v[82:83], v[2:3], v[102:103]
	v_pk_fma_f32 v[104:105], v[84:85], v[4:5], v[104:105]
	v_cmp_eq_u32_e32 vcc, 16, v52
	v_add_f32_e32 v68, v102, v103
	v_add_f32_e32 v69, v105, v104
	v_cndmask_b32_e64 v55, 0, 1.0, vcc
	v_add_f32_e32 v68, v68, v69
	v_sub_f32_e32 v86, v55, v68
	ds_read_b128 v[26:29], v106 offset:4608
	ds_read_b128 v[32:35], v106 offset:4624
	ds_read_b128 v[36:39], v106 offset:4640
	ds_read_b128 v[40:43], v106 offset:4656
	ds_read_b128 v[56:59], v106 offset:4672
	s_waitcnt lgkmcnt(9)
	v_pk_mul_f32 v[102:103], v[70:71], v[6:7]
	v_pk_mul_f32 v[104:105], v[72:73], v[8:9]
	s_waitcnt lgkmcnt(8)
	v_pk_fma_f32 v[102:103], v[74:75], v[10:11], v[102:103]
	v_pk_fma_f32 v[104:105], v[76:77], v[12:13], v[104:105]
	s_waitcnt lgkmcnt(7)
	v_pk_fma_f32 v[102:103], v[78:79], v[14:15], v[102:103]
	v_pk_fma_f32 v[104:105], v[80:81], v[16:17], v[104:105]
	s_waitcnt lgkmcnt(6)
	v_pk_fma_f32 v[102:103], v[82:83], v[18:19], v[102:103]
	v_pk_fma_f32 v[104:105], v[84:85], v[20:21], v[104:105]
	s_waitcnt lgkmcnt(5)
	v_pk_fma_f32 v[102:103], v[86:87], v[22:23], v[102:103]
	v_cmp_eq_u32_e32 vcc, 17, v52
	v_add_f32_e32 v68, v102, v103
	v_add_f32_e32 v69, v105, v104
	v_cndmask_b32_e64 v55, 0, 1.0, vcc
	v_add_f32_e32 v68, v68, v69
	v_sub_f32_e32 v87, v55, v68
	ds_read_b128 v[60:63], v106 offset:4864
	ds_read_b128 v[64:67], v106 offset:4880
	ds_read_b128 v[2:5], v106 offset:4896
	ds_read_b128 v[6:9], v106 offset:4912
	ds_read_b128 v[10:13], v106 offset:4928
	s_waitcnt lgkmcnt(9)
	v_pk_mul_f32 v[102:103], v[70:71], v[26:27]
	v_pk_mul_f32 v[104:105], v[72:73], v[28:29]
	s_waitcnt lgkmcnt(8)
	v_pk_fma_f32 v[102:103], v[74:75], v[32:33], v[102:103]
	v_pk_fma_f32 v[104:105], v[76:77], v[34:35], v[104:105]
	s_waitcnt lgkmcnt(7)
	v_pk_fma_f32 v[102:103], v[78:79], v[36:37], v[102:103]
	v_pk_fma_f32 v[104:105], v[80:81], v[38:39], v[104:105]
	s_waitcnt lgkmcnt(6)
	v_pk_fma_f32 v[102:103], v[82:83], v[40:41], v[102:103]
	v_pk_fma_f32 v[104:105], v[84:85], v[42:43], v[104:105]
	s_waitcnt lgkmcnt(5)
	v_pk_fma_f32 v[102:103], v[86:87], v[56:57], v[102:103]
	v_cmp_eq_u32_e32 vcc, 18, v52
	v_add_f32_e32 v68, v102, v103
	v_add_f32_e32 v69, v105, v104
	v_cndmask_b32_e64 v55, 0, 1.0, vcc
	v_add_f32_e32 v68, v68, v69
	v_sub_f32_e32 v88, v55, v68
	ds_read_b128 v[14:17], v106 offset:5120
	ds_read_b128 v[18:21], v106 offset:5136
	ds_read_b128 v[22:25], v106 offset:5152
	ds_read_b128 v[26:29], v106 offset:5168
	ds_read_b128 v[32:35], v106 offset:5184
	s_waitcnt lgkmcnt(9)
	v_pk_mul_f32 v[102:103], v[70:71], v[60:61]
	v_pk_mul_f32 v[104:105], v[72:73], v[62:63]
	s_waitcnt lgkmcnt(8)
	v_pk_fma_f32 v[102:103], v[74:75], v[64:65], v[102:103]
	v_pk_fma_f32 v[104:105], v[76:77], v[66:67], v[104:105]
	s_waitcnt lgkmcnt(7)
	v_pk_fma_f32 v[102:103], v[78:79], v[2:3], v[102:103]
	v_pk_fma_f32 v[104:105], v[80:81], v[4:5], v[104:105]
	s_waitcnt lgkmcnt(6)
	v_pk_fma_f32 v[102:103], v[82:83], v[6:7], v[102:103]
	v_pk_fma_f32 v[104:105], v[84:85], v[8:9], v[104:105]
	s_waitcnt lgkmcnt(5)
	v_pk_fma_f32 v[102:103], v[86:87], v[10:11], v[102:103]
	v_pk_fma_f32 v[104:105], v[88:89], v[12:13], v[104:105]
	v_cmp_eq_u32_e32 vcc, 19, v52
	v_add_f32_e32 v68, v102, v103
	v_add_f32_e32 v69, v105, v104
	v_cndmask_b32_e64 v55, 0, 1.0, vcc
	v_add_f32_e32 v68, v68, v69
	v_sub_f32_e32 v89, v55, v68
	ds_read_b128 v[36:39], v106 offset:5376
	ds_read_b128 v[40:43], v106 offset:5392
	ds_read_b128 v[56:59], v106 offset:5408
	ds_read_b128 v[60:63], v106 offset:5424
	ds_read_b128 v[64:67], v106 offset:5440
	ds_read_b128 v[2:5], v106 offset:5456
	s_waitcnt lgkmcnt(10)
	v_pk_mul_f32 v[102:103], v[70:71], v[14:15]
	v_pk_mul_f32 v[104:105], v[72:73], v[16:17]
	s_waitcnt lgkmcnt(9)
	v_pk_fma_f32 v[102:103], v[74:75], v[18:19], v[102:103]
	v_pk_fma_f32 v[104:105], v[76:77], v[20:21], v[104:105]
	s_waitcnt lgkmcnt(8)
	v_pk_fma_f32 v[102:103], v[78:79], v[22:23], v[102:103]
	v_pk_fma_f32 v[104:105], v[80:81], v[24:25], v[104:105]
	s_waitcnt lgkmcnt(7)
	v_pk_fma_f32 v[102:103], v[82:83], v[26:27], v[102:103]
	v_pk_fma_f32 v[104:105], v[84:85], v[28:29], v[104:105]
	s_waitcnt lgkmcnt(6)
	v_pk_fma_f32 v[102:103], v[86:87], v[32:33], v[102:103]
	v_pk_fma_f32 v[104:105], v[88:89], v[34:35], v[104:105]
	v_cmp_eq_u32_e32 vcc, 20, v52
	v_add_f32_e32 v68, v102, v103
	v_add_f32_e32 v69, v105, v104
	v_cndmask_b32_e64 v55, 0, 1.0, vcc
	v_add_f32_e32 v68, v68, v69
	v_sub_f32_e32 v90, v55, v68
	ds_read_b128 v[6:9], v106 offset:5632
	ds_read_b128 v[10:13], v106 offset:5648
	ds_read_b128 v[14:17], v106 offset:5664
	ds_read_b128 v[18:21], v106 offset:5680
	ds_read_b128 v[22:25], v106 offset:5696
	ds_read_b128 v[26:29], v106 offset:5712
	s_waitcnt lgkmcnt(11)
	v_pk_mul_f32 v[102:103], v[70:71], v[36:37]
	v_pk_mul_f32 v[104:105], v[72:73], v[38:39]
	s_waitcnt lgkmcnt(10)
	v_pk_fma_f32 v[102:103], v[74:75], v[40:41], v[102:103]
	v_pk_fma_f32 v[104:105], v[76:77], v[42:43], v[104:105]
	s_waitcnt lgkmcnt(9)
	v_pk_fma_f32 v[102:103], v[78:79], v[56:57], v[102:103]
	v_pk_fma_f32 v[104:105], v[80:81], v[58:59], v[104:105]
	s_waitcnt lgkmcnt(8)
	v_pk_fma_f32 v[102:103], v[82:83], v[60:61], v[102:103]
	v_pk_fma_f32 v[104:105], v[84:85], v[62:63], v[104:105]
	s_waitcnt lgkmcnt(7)
	v_pk_fma_f32 v[102:103], v[86:87], v[64:65], v[102:103]
	v_pk_fma_f32 v[104:105], v[88:89], v[66:67], v[104:105]
	s_waitcnt lgkmcnt(6)
	v_pk_fma_f32 v[102:103], v[90:91], v[2:3], v[102:103]
	v_cmp_eq_u32_e32 vcc, 21, v52
	v_add_f32_e32 v68, v102, v103
	v_add_f32_e32 v69, v105, v104
	v_cndmask_b32_e64 v55, 0, 1.0, vcc
	v_add_f32_e32 v68, v68, v69
	v_sub_f32_e32 v91, v55, v68
	ds_read_b128 v[32:35], v106 offset:5888
	ds_read_b128 v[36:39], v106 offset:5904
	ds_read_b128 v[40:43], v106 offset:5920
	ds_read_b128 v[56:59], v106 offset:5936
	ds_read_b128 v[60:63], v106 offset:5952
	ds_read_b128 v[64:67], v106 offset:5968
	s_waitcnt lgkmcnt(11)
	v_pk_mul_f32 v[102:103], v[70:71], v[6:7]
	v_pk_mul_f32 v[104:105], v[72:73], v[8:9]
	s_waitcnt lgkmcnt(10)
	v_pk_fma_f32 v[102:103], v[74:75], v[10:11], v[102:103]
	v_pk_fma_f32 v[104:105], v[76:77], v[12:13], v[104:105]
	s_waitcnt lgkmcnt(9)
	v_pk_fma_f32 v[102:103], v[78:79], v[14:15], v[102:103]
	v_pk_fma_f32 v[104:105], v[80:81], v[16:17], v[104:105]
	s_waitcnt lgkmcnt(8)
	v_pk_fma_f32 v[102:103], v[82:83], v[18:19], v[102:103]
	v_pk_fma_f32 v[104:105], v[84:85], v[20:21], v[104:105]
	s_waitcnt lgkmcnt(7)
	v_pk_fma_f32 v[102:103], v[86:87], v[22:23], v[102:103]
	v_pk_fma_f32 v[104:105], v[88:89], v[24:25], v[104:105]
	s_waitcnt lgkmcnt(6)
	v_pk_fma_f32 v[102:103], v[90:91], v[26:27], v[102:103]
	v_cmp_eq_u32_e32 vcc, 22, v52
	v_add_f32_e32 v68, v102, v103
	v_add_f32_e32 v69, v105, v104
	v_cndmask_b32_e64 v55, 0, 1.0, vcc
	v_add_f32_e32 v68, v68, v69
	v_sub_f32_e32 v92, v55, v68
	ds_read_b128 v[2:5], v106 offset:6144
	ds_read_b128 v[6:9], v106 offset:6160
	ds_read_b128 v[10:13], v106 offset:6176
	ds_read_b128 v[14:17], v106 offset:6192
	ds_read_b128 v[18:21], v106 offset:6208
	ds_read_b128 v[22:25], v106 offset:6224
	s_waitcnt lgkmcnt(11)
	v_pk_mul_f32 v[102:103], v[70:71], v[32:33]
	v_pk_mul_f32 v[104:105], v[72:73], v[34:35]
	s_waitcnt lgkmcnt(10)
	v_pk_fma_f32 v[102:103], v[74:75], v[36:37], v[102:103]
	v_pk_fma_f32 v[104:105], v[76:77], v[38:39], v[104:105]
	s_waitcnt lgkmcnt(9)
	v_pk_fma_f32 v[102:103], v[78:79], v[40:41], v[102:103]
	v_pk_fma_f32 v[104:105], v[80:81], v[42:43], v[104:105]
	s_waitcnt lgkmcnt(8)
	v_pk_fma_f32 v[102:103], v[82:83], v[56:57], v[102:103]
	v_pk_fma_f32 v[104:105], v[84:85], v[58:59], v[104:105]
	s_waitcnt lgkmcnt(7)
	v_pk_fma_f32 v[102:103], v[86:87], v[60:61], v[102:103]
	v_pk_fma_f32 v[104:105], v[88:89], v[62:63], v[104:105]
	s_waitcnt lgkmcnt(6)
	v_pk_fma_f32 v[102:103], v[90:91], v[64:65], v[102:103]
	v_pk_fma_f32 v[104:105], v[92:93], v[66:67], v[104:105]
	v_cmp_eq_u32_e32 vcc, 23, v52
	v_add_f32_e32 v68, v102, v103
	v_add_f32_e32 v69, v105, v104
	v_cndmask_b32_e64 v55, 0, 1.0, vcc
	v_add_f32_e32 v68, v68, v69
	v_sub_f32_e32 v93, v55, v68
	ds_read_b128 v[26:29], v106 offset:6400
	ds_read_b128 v[32:35], v106 offset:6416
	ds_read_b128 v[36:39], v106 offset:6432
	ds_read_b128 v[40:43], v106 offset:6448
	ds_read_b128 v[56:59], v106 offset:6464
	ds_read_b128 v[60:63], v106 offset:6480
	ds_read_b128 v[64:67], v106 offset:6496
	s_waitcnt lgkmcnt(12)
	v_pk_mul_f32 v[102:103], v[70:71], v[2:3]
	v_pk_mul_f32 v[104:105], v[72:73], v[4:5]
	s_waitcnt lgkmcnt(11)
	v_pk_fma_f32 v[102:103], v[74:75], v[6:7], v[102:103]
	v_pk_fma_f32 v[104:105], v[76:77], v[8:9], v[104:105]
	s_waitcnt lgkmcnt(10)
	v_pk_fma_f32 v[102:103], v[78:79], v[10:11], v[102:103]
	v_pk_fma_f32 v[104:105], v[80:81], v[12:13], v[104:105]
	s_waitcnt lgkmcnt(9)
	v_pk_fma_f32 v[102:103], v[82:83], v[14:15], v[102:103]
	v_pk_fma_f32 v[104:105], v[84:85], v[16:17], v[104:105]
	s_waitcnt lgkmcnt(8)
	v_pk_fma_f32 v[102:103], v[86:87], v[18:19], v[102:103]
	v_pk_fma_f32 v[104:105], v[88:89], v[20:21], v[104:105]
	s_waitcnt lgkmcnt(7)
	v_pk_fma_f32 v[102:103], v[90:91], v[22:23], v[102:103]
	v_pk_fma_f32 v[104:105], v[92:93], v[24:25], v[104:105]
	v_cmp_eq_u32_e32 vcc, 24, v52
	v_add_f32_e32 v68, v102, v103
	v_add_f32_e32 v69, v105, v104
	v_cndmask_b32_e64 v55, 0, 1.0, vcc
	v_add_f32_e32 v68, v68, v69
	v_sub_f32_e32 v94, v55, v68
	ds_read_b128 v[2:5], v106 offset:6656
	ds_read_b128 v[6:9], v106 offset:6672
	ds_read_b128 v[10:13], v106 offset:6688
	ds_read_b128 v[14:17], v106 offset:6704
	ds_read_b128 v[18:21], v106 offset:6720
	ds_read_b128 v[22:25], v106 offset:6736
	s_waitcnt lgkmcnt(12)
	v_pk_mul_f32 v[102:103], v[70:71], v[26:27]
	v_pk_mul_f32 v[104:105], v[72:73], v[28:29]
	ds_read_b128 v[26:29], v106 offset:6752
	s_waitcnt lgkmcnt(12)
	v_pk_fma_f32 v[102:103], v[74:75], v[32:33], v[102:103]
	v_pk_fma_f32 v[104:105], v[76:77], v[34:35], v[104:105]
	s_waitcnt lgkmcnt(11)
	v_pk_fma_f32 v[102:103], v[78:79], v[36:37], v[102:103]
	v_pk_fma_f32 v[104:105], v[80:81], v[38:39], v[104:105]
	s_waitcnt lgkmcnt(10)
	v_pk_fma_f32 v[102:103], v[82:83], v[40:41], v[102:103]
	v_pk_fma_f32 v[104:105], v[84:85], v[42:43], v[104:105]
	s_waitcnt lgkmcnt(9)
	v_pk_fma_f32 v[102:103], v[86:87], v[56:57], v[102:103]
	v_pk_fma_f32 v[104:105], v[88:89], v[58:59], v[104:105]
	s_waitcnt lgkmcnt(8)
	v_pk_fma_f32 v[102:103], v[90:91], v[60:61], v[102:103]
	v_pk_fma_f32 v[104:105], v[92:93], v[62:63], v[104:105]
	s_waitcnt lgkmcnt(7)
	v_pk_fma_f32 v[102:103], v[94:95], v[64:65], v[102:103]
	v_cmp_eq_u32_e32 vcc, 25, v52
	v_add_f32_e32 v68, v102, v103
	v_add_f32_e32 v69, v105, v104
	v_cndmask_b32_e64 v55, 0, 1.0, vcc
	v_add_f32_e32 v68, v68, v69
	v_sub_f32_e32 v95, v55, v68
	ds_read_b128 v[32:35], v106 offset:6912
	ds_read_b128 v[36:39], v106 offset:6928
	ds_read_b128 v[40:43], v106 offset:6944
	ds_read_b128 v[56:59], v106 offset:6960
	ds_read_b128 v[60:63], v106 offset:6976
	ds_read_b128 v[64:67], v106 offset:6992
	s_waitcnt lgkmcnt(12)
	v_pk_mul_f32 v[102:103], v[70:71], v[2:3]
	v_pk_mul_f32 v[104:105], v[72:73], v[4:5]
	ds_read_b128 v[2:5], v106 offset:7008
	s_waitcnt lgkmcnt(12)
	v_pk_fma_f32 v[102:103], v[74:75], v[6:7], v[102:103]
	v_pk_fma_f32 v[104:105], v[76:77], v[8:9], v[104:105]
	s_waitcnt lgkmcnt(11)
	v_pk_fma_f32 v[102:103], v[78:79], v[10:11], v[102:103]
	v_pk_fma_f32 v[104:105], v[80:81], v[12:13], v[104:105]
	s_waitcnt lgkmcnt(10)
	v_pk_fma_f32 v[102:103], v[82:83], v[14:15], v[102:103]
	v_pk_fma_f32 v[104:105], v[84:85], v[16:17], v[104:105]
	s_waitcnt lgkmcnt(9)
	v_pk_fma_f32 v[102:103], v[86:87], v[18:19], v[102:103]
	v_pk_fma_f32 v[104:105], v[88:89], v[20:21], v[104:105]
	s_waitcnt lgkmcnt(8)
	v_pk_fma_f32 v[102:103], v[90:91], v[22:23], v[102:103]
	v_pk_fma_f32 v[104:105], v[92:93], v[24:25], v[104:105]
	s_waitcnt lgkmcnt(7)
	v_pk_fma_f32 v[102:103], v[94:95], v[26:27], v[102:103]
	v_cmp_eq_u32_e32 vcc, 26, v52
	v_add_f32_e32 v68, v102, v103
	v_add_f32_e32 v69, v105, v104
	v_cndmask_b32_e64 v55, 0, 1.0, vcc
	v_add_f32_e32 v68, v68, v69
	v_sub_f32_e32 v96, v55, v68
	ds_read_b128 v[6:9], v106 offset:7168
	ds_read_b128 v[10:13], v106 offset:7184
	ds_read_b128 v[14:17], v106 offset:7200
	ds_read_b128 v[18:21], v106 offset:7216
	ds_read_b128 v[22:25], v106 offset:7232
	ds_read_b128 v[26:29], v106 offset:7248
	s_waitcnt lgkmcnt(12)
	v_pk_mul_f32 v[102:103], v[70:71], v[32:33]
	v_pk_mul_f32 v[104:105], v[72:73], v[34:35]
	ds_read_b128 v[32:35], v106 offset:7264
	s_waitcnt lgkmcnt(12)
	v_pk_fma_f32 v[102:103], v[74:75], v[36:37], v[102:103]
	v_pk_fma_f32 v[104:105], v[76:77], v[38:39], v[104:105]
	s_waitcnt lgkmcnt(11)
	v_pk_fma_f32 v[102:103], v[78:79], v[40:41], v[102:103]
	v_pk_fma_f32 v[104:105], v[80:81], v[42:43], v[104:105]
	s_waitcnt lgkmcnt(10)
	v_pk_fma_f32 v[102:103], v[82:83], v[56:57], v[102:103]
	v_pk_fma_f32 v[104:105], v[84:85], v[58:59], v[104:105]
	s_waitcnt lgkmcnt(9)
	v_pk_fma_f32 v[102:103], v[86:87], v[60:61], v[102:103]
	v_pk_fma_f32 v[104:105], v[88:89], v[62:63], v[104:105]
	s_waitcnt lgkmcnt(8)
	v_pk_fma_f32 v[102:103], v[90:91], v[64:65], v[102:103]
	v_pk_fma_f32 v[104:105], v[92:93], v[66:67], v[104:105]
	s_waitcnt lgkmcnt(7)
	v_pk_fma_f32 v[102:103], v[94:95], v[2:3], v[102:103]
	v_pk_fma_f32 v[104:105], v[96:97], v[4:5], v[104:105]
	v_cmp_eq_u32_e32 vcc, 27, v52
	v_add_f32_e32 v68, v102, v103
	v_add_f32_e32 v69, v105, v104
	v_cndmask_b32_e64 v55, 0, 1.0, vcc
	v_add_f32_e32 v68, v68, v69
	v_sub_f32_e32 v97, v55, v68
	ds_read_b128 v[36:39], v106 offset:7424
	ds_read_b128 v[40:43], v106 offset:7440
	ds_read_b128 v[56:59], v106 offset:7456
	ds_read_b128 v[60:63], v106 offset:7472
	ds_read_b128 v[64:67], v106 offset:7488
	ds_read_b128 v[2:5], v106 offset:7504
	s_waitcnt lgkmcnt(12)
	v_pk_mul_f32 v[102:103], v[70:71], v[6:7]
	v_pk_mul_f32 v[104:105], v[72:73], v[8:9]
	ds_read_b128 v[6:9], v106 offset:7520
	s_waitcnt lgkmcnt(12)
	v_pk_fma_f32 v[102:103], v[74:75], v[10:11], v[102:103]
	v_pk_fma_f32 v[104:105], v[76:77], v[12:13], v[104:105]
	ds_read_b128 v[10:13], v106 offset:7536
	s_waitcnt lgkmcnt(12)
	v_pk_fma_f32 v[102:103], v[78:79], v[14:15], v[102:103]
	v_pk_fma_f32 v[104:105], v[80:81], v[16:17], v[104:105]
	s_waitcnt lgkmcnt(11)
	v_pk_fma_f32 v[102:103], v[82:83], v[18:19], v[102:103]
	v_pk_fma_f32 v[104:105], v[84:85], v[20:21], v[104:105]
	s_waitcnt lgkmcnt(10)
	v_pk_fma_f32 v[102:103], v[86:87], v[22:23], v[102:103]
	v_pk_fma_f32 v[104:105], v[88:89], v[24:25], v[104:105]
	s_waitcnt lgkmcnt(9)
	v_pk_fma_f32 v[102:103], v[90:91], v[26:27], v[102:103]
	v_pk_fma_f32 v[104:105], v[92:93], v[28:29], v[104:105]
	s_waitcnt lgkmcnt(8)
	v_pk_fma_f32 v[102:103], v[94:95], v[32:33], v[102:103]
	v_pk_fma_f32 v[104:105], v[96:97], v[34:35], v[104:105]
	v_cmp_eq_u32_e32 vcc, 28, v52
	v_add_f32_e32 v68, v102, v103
	v_add_f32_e32 v69, v105, v104
	v_cndmask_b32_e64 v55, 0, 1.0, vcc
	v_add_f32_e32 v68, v68, v69
	v_sub_f32_e32 v98, v55, v68
	ds_read_b128 v[14:17], v106 offset:7680
	ds_read_b128 v[18:21], v106 offset:7696
	ds_read_b128 v[22:25], v106 offset:7712
	ds_read_b128 v[26:29], v106 offset:7728
	ds_read_b128 v[32:35], v106 offset:7744
	s_waitcnt lgkmcnt(12)
	v_pk_mul_f32 v[102:103], v[70:71], v[36:37]
	v_pk_mul_f32 v[104:105], v[72:73], v[38:39]
	ds_read_b128 v[36:39], v106 offset:7760
	s_waitcnt lgkmcnt(12)
	v_pk_fma_f32 v[102:103], v[74:75], v[40:41], v[102:103]
	v_pk_fma_f32 v[104:105], v[76:77], v[42:43], v[104:105]
	ds_read_b128 v[40:43], v106 offset:7776
	s_waitcnt lgkmcnt(12)
	v_pk_fma_f32 v[102:103], v[78:79], v[56:57], v[102:103]
	v_pk_fma_f32 v[104:105], v[80:81], v[58:59], v[104:105]
	ds_read_b128 v[56:59], v106 offset:7792
	s_waitcnt lgkmcnt(12)
	v_pk_fma_f32 v[102:103], v[82:83], v[60:61], v[102:103]
	v_pk_fma_f32 v[104:105], v[84:85], v[62:63], v[104:105]
	s_waitcnt lgkmcnt(11)
	v_pk_fma_f32 v[102:103], v[86:87], v[64:65], v[102:103]
	v_pk_fma_f32 v[104:105], v[88:89], v[66:67], v[104:105]
	s_waitcnt lgkmcnt(10)
	v_pk_fma_f32 v[102:103], v[90:91], v[2:3], v[102:103]
	v_pk_fma_f32 v[104:105], v[92:93], v[4:5], v[104:105]
	s_waitcnt lgkmcnt(9)
	v_pk_fma_f32 v[102:103], v[94:95], v[6:7], v[102:103]
	v_pk_fma_f32 v[104:105], v[96:97], v[8:9], v[104:105]
	s_waitcnt lgkmcnt(8)
	v_pk_fma_f32 v[102:103], v[98:99], v[10:11], v[102:103]
	v_cmp_eq_u32_e32 vcc, 29, v52
	v_add_f32_e32 v68, v102, v103
	v_add_f32_e32 v69, v105, v104
	v_cndmask_b32_e64 v55, 0, 1.0, vcc
	v_add_f32_e32 v68, v68, v69
	v_sub_f32_e32 v99, v55, v68
	ds_read_b128 v[60:63], v106 offset:7936
	ds_read_b128 v[64:67], v106 offset:7952
	ds_read_b128 v[2:5], v106 offset:7968
	ds_read_b128 v[6:9], v106 offset:7984
	ds_read_b128 v[10:13], v106 offset:8000
	s_waitcnt lgkmcnt(12)
	v_pk_mul_f32 v[102:103], v[70:71], v[14:15]
	v_pk_mul_f32 v[104:105], v[72:73], v[16:17]
	ds_read_b128 v[14:17], v106 offset:8016
	s_waitcnt lgkmcnt(12)
	v_pk_fma_f32 v[102:103], v[74:75], v[18:19], v[102:103]
	v_pk_fma_f32 v[104:105], v[76:77], v[20:21], v[104:105]
	ds_read_b128 v[18:21], v106 offset:8032
	s_waitcnt lgkmcnt(12)
	v_pk_fma_f32 v[102:103], v[78:79], v[22:23], v[102:103]
	v_pk_fma_f32 v[104:105], v[80:81], v[24:25], v[104:105]
	ds_read_b128 v[22:25], v106 offset:8048
	s_waitcnt lgkmcnt(12)
	v_pk_fma_f32 v[102:103], v[82:83], v[26:27], v[102:103]
	v_pk_fma_f32 v[104:105], v[84:85], v[28:29], v[104:105]
	s_waitcnt lgkmcnt(11)
	v_pk_fma_f32 v[102:103], v[86:87], v[32:33], v[102:103]
	v_pk_fma_f32 v[104:105], v[88:89], v[34:35], v[104:105]
	s_waitcnt lgkmcnt(10)
	v_pk_fma_f32 v[102:103], v[90:91], v[36:37], v[102:103]
	v_pk_fma_f32 v[104:105], v[92:93], v[38:39], v[104:105]
	s_waitcnt lgkmcnt(9)
	v_pk_fma_f32 v[102:103], v[94:95], v[40:41], v[102:103]
	v_pk_fma_f32 v[104:105], v[96:97], v[42:43], v[104:105]
	s_waitcnt lgkmcnt(8)
	v_pk_fma_f32 v[102:103], v[98:99], v[56:57], v[102:103]
	v_cmp_eq_u32_e32 vcc, 30, v52
	v_add_f32_e32 v68, v102, v103
	v_add_f32_e32 v69, v105, v104
	v_cndmask_b32_e64 v55, 0, 1.0, vcc
	v_add_f32_e32 v68, v68, v69
	v_sub_f32_e32 v100, v55, v68
	s_waitcnt lgkmcnt(7)
	v_pk_mul_f32 v[102:103], v[70:71], v[60:61]
	v_pk_mul_f32 v[104:105], v[72:73], v[62:63]
	s_waitcnt lgkmcnt(6)
	v_pk_fma_f32 v[102:103], v[74:75], v[64:65], v[102:103]
	v_pk_fma_f32 v[104:105], v[76:77], v[66:67], v[104:105]
	s_waitcnt lgkmcnt(5)
	v_pk_fma_f32 v[102:103], v[78:79], v[2:3], v[102:103]
	v_pk_fma_f32 v[104:105], v[80:81], v[4:5], v[104:105]
	s_waitcnt lgkmcnt(4)
	v_pk_fma_f32 v[102:103], v[82:83], v[6:7], v[102:103]
	v_pk_fma_f32 v[104:105], v[84:85], v[8:9], v[104:105]
	s_waitcnt lgkmcnt(3)
	v_pk_fma_f32 v[102:103], v[86:87], v[10:11], v[102:103]
	v_pk_fma_f32 v[104:105], v[88:89], v[12:13], v[104:105]
	s_waitcnt lgkmcnt(2)
	v_pk_fma_f32 v[102:103], v[90:91], v[14:15], v[102:103]
	v_pk_fma_f32 v[104:105], v[92:93], v[16:17], v[104:105]
	s_waitcnt lgkmcnt(1)
	v_pk_fma_f32 v[102:103], v[94:95], v[18:19], v[102:103]
	v_pk_fma_f32 v[104:105], v[96:97], v[20:21], v[104:105]
	s_waitcnt lgkmcnt(0)
	v_pk_fma_f32 v[102:103], v[98:99], v[22:23], v[102:103]
	v_pk_fma_f32 v[104:105], v[100:101], v[24:25], v[104:105]
	v_cmp_eq_u32_e32 vcc, 31, v52
	v_add_f32_e32 v68, v102, v103
	v_add_f32_e32 v69, v105, v104
	v_cndmask_b32_e64 v55, 0, 1.0, vcc
	v_add_f32_e32 v68, v68, v69
	v_sub_f32_e32 v101, v55, v68
	v_mov_b32_e32 v32, v70
	v_mov_b32_e32 v31, v71
	v_mov_b32_e32 v33, v72
	v_mov_b32_e32 v34, v73
	v_mov_b32_e32 v35, v74
	v_mov_b32_e32 v36, v75
	v_mov_b32_e32 v37, v76
	v_mov_b32_e32 v38, v77
	v_mov_b32_e32 v39, v78
	v_mov_b32_e32 v40, v79
	v_mov_b32_e32 v41, v80
	v_mov_b32_e32 v42, v81
	v_mov_b32_e32 v43, v82
	v_mov_b32_e32 v44, v83
	v_mov_b32_e32 v45, v84
	v_mov_b32_e32 v48, v85
	v_mov_b32_e32 v49, v86
	v_mov_b32_e32 v55, v87
	v_mov_b32_e32 v56, v88
	v_mov_b32_e32 v57, v89
	v_mov_b32_e32 v58, v90
	v_mov_b32_e32 v59, v91
	v_mov_b32_e32 v60, v92
	v_mov_b32_e32 v61, v93
	v_mov_b32_e32 v62, v94
	v_mov_b32_e32 v63, v95
	v_mov_b32_e32 v64, v96
	v_mov_b32_e32 v65, v97
	v_mov_b32_e32 v66, v98
	v_mov_b32_e32 v67, v99
	v_mov_b32_e32 v68, v100
	v_mov_b32_e32 v69, v101
	v_cmp_lt_u32_e32 vcc, 31, v160
	v_mul_u32_u24_e32 v2, 40, v52
	s_and_saveexec_b64 s[22:23], vcc
	s_xor_b64 s[22:23], exec, s[22:23]
	s_cbranch_execz .LBB0_613
	v_cvt_pk_bf16_f32 v2, v32, s0
	v_lshl_add_u32 v3, v52, 1, v146
	ds_write_b16 v3, v2 offset:18944
	v_cvt_pk_bf16_f32 v2, v31, s0
	ds_write_b16 v3, v2 offset:19024
	v_cvt_pk_bf16_f32 v2, v33, s0
	ds_write_b16 v3, v2 offset:19104
	v_cvt_pk_bf16_f32 v2, v34, s0
	ds_write_b16 v3, v2 offset:19184
	v_cvt_pk_bf16_f32 v2, v35, s0
	ds_write_b16 v3, v2 offset:19264
	v_cvt_pk_bf16_f32 v2, v36, s0
	ds_write_b16 v3, v2 offset:19344
	v_cvt_pk_bf16_f32 v2, v37, s0
	ds_write_b16 v3, v2 offset:19424
	v_cvt_pk_bf16_f32 v2, v38, s0
	ds_write_b16 v3, v2 offset:19504
	v_cvt_pk_bf16_f32 v2, v39, s0
	ds_write_b16 v3, v2 offset:19584
	v_cvt_pk_bf16_f32 v2, v40, s0
	ds_write_b16 v3, v2 offset:19664
	v_cvt_pk_bf16_f32 v2, v41, s0
	ds_write_b16 v3, v2 offset:19744
	v_cvt_pk_bf16_f32 v2, v42, s0
	ds_write_b16 v3, v2 offset:19824
	v_cvt_pk_bf16_f32 v2, v43, s0
	ds_write_b16 v3, v2 offset:19904
	v_cvt_pk_bf16_f32 v2, v44, s0
	ds_write_b16 v3, v2 offset:19984
	v_cvt_pk_bf16_f32 v2, v45, s0
	ds_write_b16 v3, v2 offset:20064
	v_cvt_pk_bf16_f32 v2, v48, s0
	ds_write_b16 v3, v2 offset:20144
	v_cvt_pk_bf16_f32 v2, v49, s0
	ds_write_b16 v3, v2 offset:20224
	v_cvt_pk_bf16_f32 v2, v55, s0
	ds_write_b16 v3, v2 offset:20304
	v_cvt_pk_bf16_f32 v2, v56, s0
	ds_write_b16 v3, v2 offset:20384
	v_cvt_pk_bf16_f32 v2, v57, s0
	ds_write_b16 v3, v2 offset:20464
	v_cvt_pk_bf16_f32 v2, v58, s0
	ds_write_b16 v3, v2 offset:20544
	v_cvt_pk_bf16_f32 v2, v59, s0
	ds_write_b16 v3, v2 offset:20624
	v_cvt_pk_bf16_f32 v2, v60, s0
	ds_write_b16 v3, v2 offset:20704
	v_cvt_pk_bf16_f32 v2, v61, s0
	ds_write_b16 v3, v2 offset:20784
	v_cvt_pk_bf16_f32 v2, v62, s0
	ds_write_b16 v3, v2 offset:20864
	v_cvt_pk_bf16_f32 v2, v63, s0
	ds_write_b16 v3, v2 offset:20944
	v_cvt_pk_bf16_f32 v2, v64, s0
	ds_write_b16 v3, v2 offset:21024
	v_cvt_pk_bf16_f32 v2, v65, s0
	ds_write_b16 v3, v2 offset:21104
	v_cvt_pk_bf16_f32 v2, v66, s0
	ds_write_b16 v3, v2 offset:21184
	v_cvt_pk_bf16_f32 v2, v67, s0
	ds_write_b16 v3, v2 offset:21264
	v_cvt_pk_bf16_f32 v2, v68, s0
	ds_write_b16 v3, v2 offset:21344
	v_cvt_pk_bf16_f32 v2, v69, s0
	ds_write_b16 v3, v2 offset:21424
	v_mul_u32_u24_e32 v2, 40, v52
